# gla_pass1 chunk-state stores: lane-pair exchange (v_permlane16_swap) so 8 dwordx4 stores replace 16 dwordx2 stores
# speedup vs baseline: 1.0089x; 1.0032x over previous
; __device__ __forceinline__ void gla_pass1(const Ctx& cx, const Params& p, int l, int item, float* ldsf, int lane) {
;     ...
;   bfu* U = reinterpret_cast<bfu*>(p.ws + OFF_GU) + (size_t)item * 4096;
; #pragma unroll
;   for (int db = 0; db < 4; ++db)
; #pragma unroll
;     for (int vb = 0; vb < 4; ++vb) {
;       const f32x4 tv = T[db][vb];
;       *reinterpret_cast<u32x2*>(U + (16 * vb + c) * 64 + 16 * db + 4 * g) = (u32x2){pack2(tv[0], tv[1]), pack2(tv[2], tv[3])};
;     }
;   reinterpret_cast<float*>(p.ws + OFF_GG)[(size_t)item * 64 + lane] = gacc;
.LBB0_108:
	s_nop 7
	v_ashrrev_i32_e32 v125, 31, v124
	v_lshlrev_b64 v[0:1], 13, v[124:125]
	v_lshl_add_u64 v[0:1], v[114:115], 0, v[0:1]
	v_mov_b32_e32 v119, v18
	v_mov_b32_e32 v121, v18
	v_mov_b32_e32 v123, v18
	v_and_b32_e32 v2, 8, v114
	v_mul_u32_u24_e32 v2, 3, v2
	v_mov_b32_e32 v3, 0
	v_lshl_add_u64 v[0:1], v[0:1], 0, v[2:3]
	v_lshl_add_u64 v[4:5], v[0:1], 0, v[118:119]
	v_lshl_add_u64 v[6:7], v[0:1], 0, v[120:121]
	v_lshl_add_u64 v[8:9], v[0:1], 0, v[122:123]
	v_cvt_pk_bf16_f32 v80, v80, v81
	v_cvt_pk_bf16_f32 v81, v82, v83
	v_cvt_pk_bf16_f32 v82, v64, v65
	v_cvt_pk_bf16_f32 v83, v66, v67
	s_nop 1
	v_permlane16_swap_b32_e32 v80, v82
	v_permlane16_swap_b32_e32 v81, v83
	global_store_dwordx4 v[4:5], v[80:83], off
	v_cvt_pk_bf16_f32 v32, v32, v33
	v_cvt_pk_bf16_f32 v33, v34, v35
	v_cvt_pk_bf16_f32 v34, v52, v53
	v_cvt_pk_bf16_f32 v35, v54, v55
	s_nop 1
	v_permlane16_swap_b32_e32 v32, v34
	v_permlane16_swap_b32_e32 v33, v35
	global_store_dwordx4 v[4:5], v[32:35], off offset:64
	v_cvt_pk_bf16_f32 v76, v76, v77
	v_cvt_pk_bf16_f32 v77, v78, v79
	v_cvt_pk_bf16_f32 v78, v60, v61
	v_cvt_pk_bf16_f32 v79, v62, v63
	s_nop 1
	v_permlane16_swap_b32_e32 v76, v78
	v_permlane16_swap_b32_e32 v77, v79
	global_store_dwordx4 v[4:5], v[76:79], off offset:2048
	v_cvt_pk_bf16_f32 v28, v28, v29
	v_cvt_pk_bf16_f32 v29, v30, v31
	v_cvt_pk_bf16_f32 v30, v48, v49
	v_cvt_pk_bf16_f32 v31, v50, v51
	s_nop 1
	v_permlane16_swap_b32_e32 v28, v30
	v_permlane16_swap_b32_e32 v29, v31
	global_store_dwordx4 v[4:5], v[28:31], off offset:2112
	v_cvt_pk_bf16_f32 v72, v72, v73
	v_cvt_pk_bf16_f32 v73, v74, v75
	v_cvt_pk_bf16_f32 v74, v56, v57
	v_cvt_pk_bf16_f32 v75, v58, v59
	s_nop 1
	v_permlane16_swap_b32_e32 v72, v74
	v_permlane16_swap_b32_e32 v73, v75
	global_store_dwordx4 v[6:7], v[72:75], off
	v_cvt_pk_bf16_f32 v24, v24, v25
	v_cvt_pk_bf16_f32 v25, v26, v27
	v_cvt_pk_bf16_f32 v26, v44, v45
	v_cvt_pk_bf16_f32 v27, v46, v47
	s_nop 1
	v_permlane16_swap_b32_e32 v24, v26
	v_permlane16_swap_b32_e32 v25, v27
	global_store_dwordx4 v[6:7], v[24:27], off offset:64
	v_cvt_pk_bf16_f32 v68, v68, v69
	v_cvt_pk_bf16_f32 v69, v70, v71
	v_cvt_pk_bf16_f32 v70, v36, v37
	v_cvt_pk_bf16_f32 v71, v38, v39
	s_nop 1
	v_permlane16_swap_b32_e32 v68, v70
	v_permlane16_swap_b32_e32 v69, v71
	global_store_dwordx4 v[8:9], v[68:71], off
	v_cvt_pk_bf16_f32 v20, v20, v21
	v_cvt_pk_bf16_f32 v21, v22, v23
	v_cvt_pk_bf16_f32 v22, v40, v41
	v_cvt_pk_bf16_f32 v23, v42, v43
	s_nop 1
	v_permlane16_swap_b32_e32 v20, v22
	v_permlane16_swap_b32_e32 v21, v23
	global_store_dwordx4 v[8:9], v[20:23], off offset:64
	s_nop 1
	v_add_u32_e32 v130, s42, v130
	s_movk_i32 s0, 0x47f
	v_lshlrev_b64 v[0:1], 8, v[124:125]
	v_cmp_lt_i32_e32 vcc, s0, v130
	v_lshl_add_u64 v[0:1], v[116:117], 0, v[0:1]
	s_or_b64 s[14:15], vcc, s[14:15]
	global_store_dword v[0:1], v137, off
	s_andn2_b64 exec, exec, s[14:15]
	s_cbranch_execz .LBB0_142
